# strategy 4: one static s_setprio 1 at kernel entry for the younger wave half (waves 4-7), no per-segment flips; on top of all-to-all release
# baseline (speedup 1.0000x reference)
.LBB0_2:
	v_readfirstlane_b32 s2, v0
	s_cmp_lt_u32 s2, 0x100
	s_cbranch_scc1 .Lprio_young_skip
	s_setprio 1
